# ctx_slice output epilogues: the 4 residual loads per thread hoisted ahead of the LDS reduce (were one serialized round trip each, behind store/atomic acks)
# speedup vs baseline: 1.0213x; 1.0213x over previous
; __device__ __forceinline__ unsigned pkbf(float lo, float hi) { return pg8::cvt_pk_bf16(lo, hi); }
; __device__ __forceinline__ void ctx_slice_gemm(LAS unsigned char* lds, const bf16_t* A  , const bf16_t* Bt  , int K, ...
;     ...
;         const int t = wid, rgi = t >> 1, cg = t & 1, col = col0 + 16 * cg + r16;
;         const float gt = gate2[col];
;         const bool nxt = ng != nullptr;
;         const float gs = nxt ? ng[col] * (1.f + nsc2[col]) : 0.f;
; #pragma unroll
;         for (int q = 0; q < 4; ++q) {
;             float s = 0.f;
; #pragma unroll
;             for (int w = 0; w < 8; ++w) s += part[((w * 8 + t) * 4 + q) * 64 + lane];
;             const int rr = row0 + 16 * rgi + 4 * g4 + q;
;             const float x = res_ctx[(size_t)rr * DM + col] + gt * s;
;             dst_ctx[(size_t)rr * DM + col] = x;
;             if (nxt) {
;                 xg[(size_t)(MLAT + rr) * DM + col] = (bf16_t)(pkbf(x * gs, 0.f) & 0xffffu);
;                 float ss = x * x;
;                 ss += __shfl_xor(ss, 1); ss += __shfl_xor(ss, 2); ss += __shfl_xor(ss, 4); ss += __shfl_xor(ss, 8);
;                 if (r16 == 0) unsafeAtomicAdd(rowsq_next + MLAT + rr, ss);
;             }
.LBB0_1013:
	s_ashr_i32 s4, s4, 3
	s_and_b32 s4, s4, -16
	s_lshl_b32 s14, s14, 10
	v_bfe_u32 v0, v5, 4, 2
	s_add_i32 s4, s4, s5
	v_add_u32_e32 v9, s14, v1
	v_lshl_or_b32 v0, v0, 2, s4
	v_ashrrev_i32_e32 v81, 31, v0
	v_mov_b32_e32 v80, v0
	v_lshlrev_b64 v[80:81], 12, v[80:81]
	v_lshl_or_b32 v80, v8, 2, v80
	v_lshl_add_u64 v[80:81], s[22:23], 0, v[80:81]
	flat_load_dword v90, v[80:81]
	v_add_co_u32_e32 v82, vcc, 0x1000, v80
	s_nop 1
	v_addc_co_u32_e32 v83, vcc, 0, v81, vcc
	flat_load_dword v91, v[82:83]
	v_add_co_u32_e32 v84, vcc, 0x2000, v80
	s_nop 1
	v_addc_co_u32_e32 v85, vcc, 0, v81, vcc
	flat_load_dword v92, v[84:85]
	v_add_co_u32_e32 v86, vcc, 0x3000, v80
	s_nop 1
	v_addc_co_u32_e32 v87, vcc, 0, v81, vcc
	flat_load_dword v93, v[86:87]
	v_cmp_eq_u32_e64 s[4:5], 0, v4
	ds_read2st64_b32 v[4:5], v9 offset1:32
	v_lshlrev_b32_e32 v176, 1, v8
	v_lshl_add_u64 v[2:3], s[26:27], 0, v[176:177]
	s_and_b64 vcc, exec, s[6:7]
	s_waitcnt lgkmcnt(0)
	v_add_f32_e32 v1, 0, v4
	v_add_f32_e32 v1, v1, v5
	ds_read2st64_b32 v[4:5], v9 offset0:64 offset1:96
	s_waitcnt lgkmcnt(0)
	v_add_f32_e32 v1, v1, v4
	v_add_f32_e32 v1, v1, v5
	ds_read2st64_b32 v[4:5], v9 offset0:128 offset1:160
	s_waitcnt lgkmcnt(0)
	v_add_f32_e32 v1, v1, v4
	v_add_f32_e32 v1, v1, v5
	ds_read2st64_b32 v[4:5], v9 offset0:192 offset1:224
	s_waitcnt lgkmcnt(0)
	v_add_f32_e32 v1, v1, v4
	v_add_f32_e32 v12, v1, v5
	v_ashrrev_i32_e32 v1, 31, v0
	v_lshlrev_b64 v[10:11], 12, v[0:1]
	v_lshl_or_b32 v10, v8, 2, v10
	v_lshl_add_u64 v[4:5], s[22:23], 0, v[10:11]
	v_lshl_add_u64 v[10:11], s[20:21], 0, v[10:11]
	s_waitcnt vmcnt(0) lgkmcnt(0)
	v_mov_b32_e32 v4, v90
	v_fmac_f32_e32 v4, v7, v12
	flat_store_dword v[10:11], v4
	v_lshlrev_b64 v[10:11], 11, v[0:1]
	v_lshl_add_u64 v[2:3], v[2:3], 0, v[10:11]
	s_cbranch_vccnz .LBB0_1017
	v_add_co_u32_e32 v10, vcc, 0x2000000, v2
	v_mul_f32_e32 v5, v6, v4
	s_nop 0
	v_addc_co_u32_e32 v11, vcc, 0, v3, vcc
	v_cvt_pk_bf16_f32 v5, v5, v177
	flat_store_short v[10:11], v5
	v_and_b32_e32 v11, 64, v229
	v_xor_b32_e32 v10, 1, v229
	v_add_u32_e32 v11, 64, v11
	v_cmp_lt_i32_e32 vcc, v10, v11
	v_mul_f32_e32 v5, v4, v4
	s_nop 0
	v_cndmask_b32_e32 v10, v229, v10, vcc
	v_lshlrev_b32_e32 v10, 2, v10
	ds_bpermute_b32 v5, v10, v5
	s_waitcnt lgkmcnt(0)
	v_fmac_f32_e32 v5, v4, v4
	v_xor_b32_e32 v4, 2, v229
	v_cmp_lt_i32_e32 vcc, v4, v11
	s_nop 1
	v_cndmask_b32_e32 v4, v229, v4, vcc
	v_lshlrev_b32_e32 v4, 2, v4
	ds_bpermute_b32 v4, v4, v5
	s_waitcnt lgkmcnt(0)
	v_add_f32_e32 v4, v5, v4
	v_xor_b32_e32 v5, 4, v229
	v_cmp_lt_i32_e32 vcc, v5, v11
	s_nop 1
	v_cndmask_b32_e32 v5, v229, v5, vcc
	v_lshlrev_b32_e32 v5, 2, v5
	ds_bpermute_b32 v5, v5, v4
	s_waitcnt lgkmcnt(0)
	v_add_f32_e32 v4, v4, v5
	v_xor_b32_e32 v5, 8, v229
	v_cmp_lt_i32_e32 vcc, v5, v11
	s_nop 1
	v_cndmask_b32_e32 v5, v229, v5, vcc
	v_lshlrev_b32_e32 v5, 2, v5
	ds_bpermute_b32 v5, v5, v4
	s_and_saveexec_b64 s[14:15], s[4:5]
	s_cbranch_execz .LBB0_1016
	s_waitcnt lgkmcnt(0)
	v_add_f32_e32 v10, v4, v5
	v_lshl_add_u64 v[4:5], v[0:1], 2, s[12:13]
	flat_atomic_add_f32 v[4:5], v10

; __device__ __forceinline__ unsigned pkbf(float lo, float hi) { return pg8::cvt_pk_bf16(lo, hi); }
; __device__ __forceinline__ void ctx_slice_gemm(LAS unsigned char* lds, const bf16_t* A  , const bf16_t* Bt  , int K, ...
;     ...
;         for (int q = 0; q < 4; ++q) {
;             float s = 0.f;
; #pragma unroll
;             for (int w = 0; w < 8; ++w) s += part[((w * 8 + t) * 4 + q) * 64 + lane];
;             const int rr = row0 + 16 * rgi + 4 * g4 + q;
;             const float x = res_ctx[(size_t)rr * DM + col] + gt * s;
;             dst_ctx[(size_t)rr * DM + col] = x;
;             if (nxt) {
;                 xg[(size_t)(MLAT + rr) * DM + col] = (bf16_t)(pkbf(x * gs, 0.f) & 0xffffu);
;                 float ss = x * x;
;                 ss += __shfl_xor(ss, 1); ss += __shfl_xor(ss, 2); ss += __shfl_xor(ss, 4); ss += __shfl_xor(ss, 8);
;                 if (r16 == 0) unsafeAtomicAdd(rowsq_next + MLAT + rr, ss);
;             }
.LBB0_1017:
	s_waitcnt lgkmcnt(0)
	ds_read2st64_b32 v[4:5], v9 offset0:1 offset1:33
	s_and_b64 vcc, exec, s[6:7]
	s_waitcnt lgkmcnt(0)
	v_add_f32_e32 v1, 0, v4
	v_add_f32_e32 v1, v1, v5
	ds_read2st64_b32 v[4:5], v9 offset0:65 offset1:97
	s_waitcnt lgkmcnt(0)
	v_add_f32_e32 v1, v1, v4
	v_add_f32_e32 v1, v1, v5
	ds_read2st64_b32 v[4:5], v9 offset0:129 offset1:161
	s_waitcnt lgkmcnt(0)
	v_add_f32_e32 v1, v1, v4
	v_add_f32_e32 v1, v1, v5
	ds_read2st64_b32 v[4:5], v9 offset0:193 offset1:225
	s_waitcnt lgkmcnt(0)
	v_add_f32_e32 v1, v1, v4
	v_or_b32_e32 v4, 1, v0
	v_add_f32_e32 v14, v1, v5
	v_ashrrev_i32_e32 v5, 31, v4
	v_lshlrev_b64 v[10:11], 12, v[4:5]
	v_lshl_or_b32 v10, v8, 2, v10
	v_lshl_add_u64 v[12:13], s[22:23], 0, v[10:11]
	v_mov_b32_e32 v1, v91
	v_lshl_add_u64 v[10:11], s[20:21], 0, v[10:11]
	v_fmac_f32_e32 v1, v7, v14
	flat_store_dword v[10:11], v1
	s_cbranch_vccnz .LBB0_1021
	v_mul_f32_e32 v10, v6, v1
	v_cvt_pk_bf16_f32 v12, v10, v177
	v_add_co_u32_e32 v10, vcc, 0x2000000, v2
	s_nop 1
	v_addc_co_u32_e32 v11, vcc, 0, v3, vcc
	flat_store_short v[10:11], v12 offset:2048
	v_and_b32_e32 v12, 64, v229
	v_xor_b32_e32 v11, 1, v229
	v_add_u32_e32 v12, 64, v12
	v_cmp_lt_i32_e32 vcc, v11, v12
	v_mul_f32_e32 v10, v1, v1
	s_nop 0
	v_cndmask_b32_e32 v11, v229, v11, vcc
	v_lshlrev_b32_e32 v11, 2, v11
	ds_bpermute_b32 v10, v11, v10
	s_waitcnt lgkmcnt(0)
	v_fmac_f32_e32 v10, v1, v1
	v_xor_b32_e32 v1, 2, v229
	v_cmp_lt_i32_e32 vcc, v1, v12
	s_nop 1
	v_cndmask_b32_e32 v1, v229, v1, vcc
	v_lshlrev_b32_e32 v1, 2, v1
	ds_bpermute_b32 v1, v1, v10
	s_waitcnt lgkmcnt(0)
	v_add_f32_e32 v1, v10, v1
	v_xor_b32_e32 v10, 4, v229
	v_cmp_lt_i32_e32 vcc, v10, v12
	s_nop 1
	v_cndmask_b32_e32 v10, v229, v10, vcc
	v_lshlrev_b32_e32 v10, 2, v10
	ds_bpermute_b32 v10, v10, v1
	s_waitcnt lgkmcnt(0)
	v_add_f32_e32 v1, v1, v10
	v_xor_b32_e32 v10, 8, v229
	v_cmp_lt_i32_e32 vcc, v10, v12
	s_nop 1
	v_cndmask_b32_e32 v10, v229, v10, vcc
	v_lshlrev_b32_e32 v10, 2, v10
	ds_bpermute_b32 v10, v10, v1
	s_and_saveexec_b64 s[14:15], s[4:5]
	s_cbranch_execz .LBB0_1020
	s_waitcnt lgkmcnt(0)
	v_add_f32_e32 v1, v1, v10
	v_lshl_add_u64 v[4:5], v[4:5], 2, s[12:13]
	flat_atomic_add_f32 v[4:5], v1

; __device__ __forceinline__ unsigned pkbf(float lo, float hi) { return pg8::cvt_pk_bf16(lo, hi); }
; __device__ __forceinline__ void ctx_slice_gemm(LAS unsigned char* lds, const bf16_t* A  , const bf16_t* Bt  , int K, ...
;     ...
;         for (int q = 0; q < 4; ++q) {
;             float s = 0.f;
; #pragma unroll
;             for (int w = 0; w < 8; ++w) s += part[((w * 8 + t) * 4 + q) * 64 + lane];
;             const int rr = row0 + 16 * rgi + 4 * g4 + q;
;             const float x = res_ctx[(size_t)rr * DM + col] + gt * s;
;             dst_ctx[(size_t)rr * DM + col] = x;
;             if (nxt) {
;                 xg[(size_t)(MLAT + rr) * DM + col] = (bf16_t)(pkbf(x * gs, 0.f) & 0xffffu);
;                 float ss = x * x;
;                 ss += __shfl_xor(ss, 1); ss += __shfl_xor(ss, 2); ss += __shfl_xor(ss, 4); ss += __shfl_xor(ss, 8);
;                 if (r16 == 0) unsafeAtomicAdd(rowsq_next + MLAT + rr, ss);
;             }
.LBB0_1021:
	ds_read2st64_b32 v[4:5], v9 offset0:2 offset1:34
	s_and_b64 vcc, exec, s[6:7]
	s_waitcnt lgkmcnt(0)
	v_add_f32_e32 v1, 0, v4
	v_add_f32_e32 v1, v1, v5
	ds_read2st64_b32 v[4:5], v9 offset0:66 offset1:98
	s_waitcnt lgkmcnt(0)
	v_add_f32_e32 v1, v1, v4
	v_add_f32_e32 v1, v1, v5
	ds_read2st64_b32 v[4:5], v9 offset0:130 offset1:162
	s_waitcnt lgkmcnt(0)
	v_add_f32_e32 v1, v1, v4
	v_add_f32_e32 v1, v1, v5
	ds_read2st64_b32 v[4:5], v9 offset0:194 offset1:226
	s_waitcnt lgkmcnt(0)
	v_add_f32_e32 v1, v1, v4
	v_or_b32_e32 v4, 2, v0
	v_add_f32_e32 v14, v1, v5
	v_ashrrev_i32_e32 v5, 31, v4
	v_lshlrev_b64 v[10:11], 12, v[4:5]
	v_lshl_or_b32 v10, v8, 2, v10
	v_lshl_add_u64 v[12:13], s[22:23], 0, v[10:11]
	v_mov_b32_e32 v1, v92
	v_lshl_add_u64 v[10:11], s[20:21], 0, v[10:11]
	v_fmac_f32_e32 v1, v7, v14
	flat_store_dword v[10:11], v1
	s_cbranch_vccnz .LBB0_1025
	v_mul_f32_e32 v10, v6, v1
	v_cvt_pk_bf16_f32 v12, v10, v177
	v_add_co_u32_e32 v10, vcc, 0x2001000, v2
	s_nop 1
	v_addc_co_u32_e32 v11, vcc, 0, v3, vcc
	flat_store_short v[10:11], v12
	v_and_b32_e32 v12, 64, v229
	v_xor_b32_e32 v11, 1, v229
	v_add_u32_e32 v12, 64, v12
	v_cmp_lt_i32_e32 vcc, v11, v12
	v_mul_f32_e32 v10, v1, v1
	s_nop 0
	v_cndmask_b32_e32 v11, v229, v11, vcc
	v_lshlrev_b32_e32 v11, 2, v11
	ds_bpermute_b32 v10, v11, v10
	s_waitcnt lgkmcnt(0)
	v_fmac_f32_e32 v10, v1, v1
	v_xor_b32_e32 v1, 2, v229
	v_cmp_lt_i32_e32 vcc, v1, v12
	s_nop 1
	v_cndmask_b32_e32 v1, v229, v1, vcc
	v_lshlrev_b32_e32 v1, 2, v1
	ds_bpermute_b32 v1, v1, v10
	s_waitcnt lgkmcnt(0)
	v_add_f32_e32 v1, v10, v1
	v_xor_b32_e32 v10, 4, v229
	v_cmp_lt_i32_e32 vcc, v10, v12
	s_nop 1
	v_cndmask_b32_e32 v10, v229, v10, vcc
	v_lshlrev_b32_e32 v10, 2, v10
	ds_bpermute_b32 v10, v10, v1
	s_waitcnt lgkmcnt(0)
	v_add_f32_e32 v1, v1, v10
	v_xor_b32_e32 v10, 8, v229
	v_cmp_lt_i32_e32 vcc, v10, v12
	s_nop 1
	v_cndmask_b32_e32 v10, v229, v10, vcc
	v_lshlrev_b32_e32 v10, 2, v10
	ds_bpermute_b32 v10, v10, v1
	s_and_saveexec_b64 s[14:15], s[4:5]
	s_cbranch_execz .LBB0_1024
	s_waitcnt lgkmcnt(0)
	v_add_f32_e32 v1, v1, v10
	v_lshl_add_u64 v[4:5], v[4:5], 2, s[12:13]
	flat_atomic_add_f32 v[4:5], v1

; __device__ __forceinline__ unsigned pkbf(float lo, float hi) { return pg8::cvt_pk_bf16(lo, hi); }
; __device__ __forceinline__ void ctx_slice_gemm(LAS unsigned char* lds, const bf16_t* A  , const bf16_t* Bt  , int K, ...
;     ...
;         for (int q = 0; q < 4; ++q) {
;             float s = 0.f;
; #pragma unroll
;             for (int w = 0; w < 8; ++w) s += part[((w * 8 + t) * 4 + q) * 64 + lane];
;             const int rr = row0 + 16 * rgi + 4 * g4 + q;
;             const float x = res_ctx[(size_t)rr * DM + col] + gt * s;
;             dst_ctx[(size_t)rr * DM + col] = x;
;             if (nxt) {
;                 xg[(size_t)(MLAT + rr) * DM + col] = (bf16_t)(pkbf(x * gs, 0.f) & 0xffffu);
;                 float ss = x * x;
;                 ss += __shfl_xor(ss, 1); ss += __shfl_xor(ss, 2); ss += __shfl_xor(ss, 4); ss += __shfl_xor(ss, 8);
;                 if (r16 == 0) unsafeAtomicAdd(rowsq_next + MLAT + rr, ss);
;             }
.LBB0_1025:
	ds_read2st64_b32 v[4:5], v9 offset0:3 offset1:35
	v_or_b32_e32 v0, 3, v0
	s_and_b64 vcc, exec, s[6:7]
	s_waitcnt lgkmcnt(0)
	v_add_f32_e32 v1, 0, v4
	v_add_f32_e32 v1, v1, v5
	ds_read2st64_b32 v[4:5], v9 offset0:67 offset1:99
	s_waitcnt lgkmcnt(0)
	v_add_f32_e32 v1, v1, v4
	v_add_f32_e32 v1, v1, v5
	ds_read2st64_b32 v[4:5], v9 offset0:131 offset1:163
	s_waitcnt lgkmcnt(0)
	v_add_f32_e32 v1, v1, v4
	v_add_f32_e32 v1, v1, v5
	ds_read2st64_b32 v[4:5], v9 offset0:195 offset1:227
	s_waitcnt lgkmcnt(0)
	v_add_f32_e32 v1, v1, v4
	v_add_f32_e32 v9, v1, v5
	v_ashrrev_i32_e32 v1, 31, v0
	v_lshlrev_b64 v[10:11], 12, v[0:1]
	v_lshl_or_b32 v10, v8, 2, v10
	v_lshl_add_u64 v[4:5], s[22:23], 0, v[10:11]
	v_mov_b32_e32 v4, v93
	v_fmac_f32_e32 v4, v7, v9
	v_lshl_add_u64 v[8:9], s[20:21], 0, v[10:11]
	flat_store_dword v[8:9], v4
	s_cbranch_vccnz .LBB0_1009
	v_mul_f32_e32 v5, v6, v4
	v_add_co_u32_e32 v2, vcc, 0x2001000, v2
	v_cvt_pk_bf16_f32 v5, v5, v177
	s_nop 1
	v_addc_co_u32_e32 v3, vcc, 0, v3, vcc
	flat_store_short v[2:3], v5 offset:2048
	v_and_b32_e32 v5, 64, v229
	v_xor_b32_e32 v3, 1, v229
	v_add_u32_e32 v5, 64, v5
	v_cmp_lt_i32_e32 vcc, v3, v5
	v_mul_f32_e32 v2, v4, v4
	s_nop 0
	v_cndmask_b32_e32 v3, v229, v3, vcc
	v_lshlrev_b32_e32 v3, 2, v3
	ds_bpermute_b32 v2, v3, v2
	v_xor_b32_e32 v3, 2, v229
	v_cmp_lt_i32_e32 vcc, v3, v5
	s_waitcnt lgkmcnt(0)
	v_fmac_f32_e32 v2, v4, v4
	v_cndmask_b32_e32 v3, v229, v3, vcc
	v_lshlrev_b32_e32 v3, 2, v3
	ds_bpermute_b32 v3, v3, v2
	s_waitcnt lgkmcnt(0)
	v_add_f32_e32 v2, v2, v3
	v_xor_b32_e32 v3, 4, v229
	v_cmp_lt_i32_e32 vcc, v3, v5
	s_nop 1
	v_cndmask_b32_e32 v3, v229, v3, vcc
	v_lshlrev_b32_e32 v3, 2, v3
	ds_bpermute_b32 v3, v3, v2
	s_waitcnt lgkmcnt(0)
	v_add_f32_e32 v2, v2, v3
	v_xor_b32_e32 v3, 8, v229
	v_cmp_lt_i32_e32 vcc, v3, v5
	s_nop 1
	v_cndmask_b32_e32 v3, v229, v3, vcc
	v_lshlrev_b32_e32 v3, 2, v3
	ds_bpermute_b32 v3, v3, v2
	s_and_saveexec_b64 s[6:7], s[4:5]
	s_cbranch_execz .LBB0_1008
	s_waitcnt lgkmcnt(0)
	v_add_f32_e32 v2, v2, v3
	v_lshl_add_u64 v[0:1], v[0:1], 2, s[12:13]
	flat_atomic_add_f32 v[0:1], v2
	s_branch .LBB0_1008

; __device__ __forceinline__ void ctx_slice_gemm(LAS unsigned char* lds, const bf16_t* A  , const bf16_t* Bt  , int K, ...
;     int tid_l = threadIdx.x; asm volatile("" : "+v"(tid_l)); const int tid = tid_l, lane = tid & 63, wid = __builtin_amdgcn_readfirstlane(tid >> 6), r16 = lane & 15, g4 = lane >> 4;
;     const int row0 = (blk >> 5) * 64, col0 = (blk & 31) * 32;
;     const int kw = K >> 3, kbeg = wid * kw;
;     const bf16_t* ap = A + (size_t)(MLAT + row0 + r16) * K + kbeg + 8 * g4;
;     const bf16_t* bp = Bt + (size_t)(col0 + r16) * K + kbeg + 8 * g4;
;     const size_t a16 = (size_t)16 * K;
;     f32x4 acc[4][2];
; #pragma unroll
;     for (int i = 0; i < 4; ++i)
; #pragma unroll
;         for (int j = 0; j < 2; ++j) acc[i][j] = (f32x4){0.f, 0.f, 0.f, 0.f};
; #pragma unroll 4
;     for (int k = 0; k < kw; k += 32) {
;         bf16x8 fa[4], fb[2];
; #pragma unroll
;         for (int i = 0; i < 4; ++i) fa[i] = *(const bf16x8*)(ap + i * a16 + k);
; #pragma unroll
;         for (int j = 0; j < 2; ++j) fb[j] = *(const bf16x8*)(bp + j * a16 + k);
; #pragma unroll
;         for (int i = 0; i < 4; ++i)
; #pragma unroll
;             for (int j = 0; j < 2; ++j) acc[i][j] = __builtin_amdgcn_mfma_f32_16x16x32_bf16(fa[i], fb[j], acc[i][j], 0, 0, 0);
;     }
.LBB0_1277:
	v_mov_b32_e32 v61, v222
	s_and_b32 s13, s14, 0x3e0
	v_readfirstlane_b32 s1, v61
	v_and_b32_e32 v60, 15, v61
	s_ashr_i32 s0, s1, 6
	v_or_b32_e32 v0, s13, v60
	s_mul_i32 s26, s0, 0x160
	v_mul_u32_u24_e32 v0, 0xb00, v0
	s_and_b32 s12, s15, 0xffffffc0
	s_ashr_i32 s27, s26, 31
	v_lshlrev_b32_e32 v176, 1, v0
	s_add_i32 s17, s12, 0x4000
	v_lshl_add_u64 v[4:5], s[20:21], 0, v[176:177]
	s_lshl_b64 s[26:27], s[26:27], 1
	v_or_b32_e32 v2, s17, v60
	v_and_b32_e32 v176, 48, v61
	s_waitcnt lgkmcnt(0)
	v_mov_b64_e32 v[0:1], s[18:19]
	v_lshl_add_u64 v[4:5], v[4:5], 0, s[26:27]
	v_mad_i64_i32 v[0:1], s[28:29], v2, s3, v[0:1]
	v_lshl_add_u64 v[24:25], v[4:5], 0, v[176:177]
	v_lshl_add_u64 v[0:1], v[0:1], 0, s[26:27]
	v_add_co_u32_e32 v54, vcc, s30, v24
	v_lshl_add_u64 v[50:51], v[0:1], 0, v[176:177]
	s_nop 0
	v_addc_co_u32_e32 v55, vcc, 0, v25, vcc
	v_add_co_u32_e32 v56, vcc, s30, v50
	s_mov_b32 s17, 0x2c000
	s_nop 0
	v_addc_co_u32_e32 v57, vcc, 0, v51, vcc
	v_add_co_u32_e32 v58, vcc, s17, v50
	s_mov_b32 s17, 0x42000
	s_nop 0
	v_addc_co_u32_e32 v59, vcc, 0, v51, vcc
	v_add_co_u32_e32 v52, vcc, s17, v50
	s_nop 1
	v_addc_co_u32_e32 v53, vcc, 0, v51, vcc
	s_lshl_b32 s17, s0, 4
	s_and_b32 s17, s17, 16
	s_or_b32 s13, s13, s17
	s_ashr_i32 s1, s1, 3
	s_and_b32 s1, s1, -16
	s_add_i32 s1, s1, s12
	s_brev_b32 s12, 64
	global_load_dwordx4 v[80:83], v[50:51], off
	global_load_dwordx4 v[84:87], v[56:57], off
	global_load_dwordx4 v[88:91], v[58:59], off
	global_load_dwordx4 v[92:95], v[52:53], off
	global_load_dwordx4 v[96:99], v[24:25], off
	global_load_dwordx4 v[100:103], v[54:55], off
	global_load_dwordx4 v[104:107], v[50:51], off offset:64
	global_load_dwordx4 v[108:111], v[56:57], off offset:64
	global_load_dwordx4 v[112:115], v[58:59], off offset:64
	global_load_dwordx4 v[116:119], v[52:53], off offset:64
	global_load_dwordx4 v[120:123], v[24:25], off offset:64
	global_load_dwordx4 v[124:127], v[54:55], off offset:64
	global_load_dwordx4 v[128:131], v[50:51], off offset:128
	global_load_dwordx4 v[132:135], v[56:57], off offset:128
	global_load_dwordx4 v[136:139], v[58:59], off offset:128
	global_load_dwordx4 v[140:143], v[52:53], off offset:128
	global_load_dwordx4 v[144:147], v[24:25], off offset:128
	global_load_dwordx4 v[148:151], v[54:55], off offset:128
	s_waitcnt vmcnt(12)
	v_mfma_f32_16x16x32_bf16 v[62:65], v[80:83], v[96:99], 0
	v_mfma_f32_16x16x32_bf16 v[66:69], v[80:83], v[100:103], 0
	v_mfma_f32_16x16x32_bf16 v[70:73], v[84:87], v[96:99], 0
	v_mfma_f32_16x16x32_bf16 v[74:77], v[84:87], v[100:103], 0
	v_mfma_f32_16x16x32_bf16 v[26:29], v[88:91], v[96:99], 0
	v_mfma_f32_16x16x32_bf16 v[30:33], v[88:91], v[100:103], 0
	v_mfma_f32_16x16x32_bf16 v[34:37], v[92:95], v[96:99], 0
	v_mfma_f32_16x16x32_bf16 v[38:41], v[92:95], v[100:103], 0
	global_load_dwordx4 v[80:83], v[50:51], off offset:192
	global_load_dwordx4 v[84:87], v[56:57], off offset:192
	global_load_dwordx4 v[88:91], v[58:59], off offset:192
	global_load_dwordx4 v[92:95], v[52:53], off offset:192
	global_load_dwordx4 v[96:99], v[24:25], off offset:192
	global_load_dwordx4 v[100:103], v[54:55], off offset:192
	s_waitcnt vmcnt(12)
	v_mfma_f32_16x16x32_bf16 v[62:65], v[104:107], v[120:123], v[62:65]
	v_mfma_f32_16x16x32_bf16 v[66:69], v[104:107], v[124:127], v[66:69]
	v_mfma_f32_16x16x32_bf16 v[70:73], v[108:111], v[120:123], v[70:73]
	v_mfma_f32_16x16x32_bf16 v[74:77], v[108:111], v[124:127], v[74:77]
	v_mfma_f32_16x16x32_bf16 v[26:29], v[112:115], v[120:123], v[26:29]
	v_mfma_f32_16x16x32_bf16 v[30:33], v[112:115], v[124:127], v[30:33]
	v_mfma_f32_16x16x32_bf16 v[34:37], v[116:119], v[120:123], v[34:37]
	v_mfma_f32_16x16x32_bf16 v[38:41], v[116:119], v[124:127], v[38:41]
	global_load_dwordx4 v[104:107], v[50:51], off offset:256
	global_load_dwordx4 v[108:111], v[56:57], off offset:256
	global_load_dwordx4 v[112:115], v[58:59], off offset:256
	global_load_dwordx4 v[116:119], v[52:53], off offset:256
	global_load_dwordx4 v[120:123], v[24:25], off offset:256
	global_load_dwordx4 v[124:127], v[54:55], off offset:256
	s_waitcnt vmcnt(12)
	v_mfma_f32_16x16x32_bf16 v[62:65], v[128:131], v[144:147], v[62:65]
	v_mfma_f32_16x16x32_bf16 v[66:69], v[128:131], v[148:151], v[66:69]
	v_mfma_f32_16x16x32_bf16 v[70:73], v[132:135], v[144:147], v[70:73]
	v_mfma_f32_16x16x32_bf16 v[74:77], v[132:135], v[148:151], v[74:77]
	v_mfma_f32_16x16x32_bf16 v[26:29], v[136:139], v[144:147], v[26:29]
	v_mfma_f32_16x16x32_bf16 v[30:33], v[136:139], v[148:151], v[30:33]
	v_mfma_f32_16x16x32_bf16 v[34:37], v[140:143], v[144:147], v[34:37]
	v_mfma_f32_16x16x32_bf16 v[38:41], v[140:143], v[148:151], v[38:41]
	global_load_dwordx4 v[128:131], v[50:51], off offset:320
	global_load_dwordx4 v[132:135], v[56:57], off offset:320
	global_load_dwordx4 v[136:139], v[58:59], off offset:320
	global_load_dwordx4 v[140:143], v[52:53], off offset:320
	global_load_dwordx4 v[144:147], v[24:25], off offset:320
	global_load_dwordx4 v[148:151], v[54:55], off offset:320
	s_waitcnt vmcnt(12)
	v_mfma_f32_16x16x32_bf16 v[62:65], v[80:83], v[96:99], v[62:65]
	v_mfma_f32_16x16x32_bf16 v[66:69], v[80:83], v[100:103], v[66:69]
	v_mfma_f32_16x16x32_bf16 v[70:73], v[84:87], v[96:99], v[70:73]
	v_mfma_f32_16x16x32_bf16 v[74:77], v[84:87], v[100:103], v[74:77]
	v_mfma_f32_16x16x32_bf16 v[26:29], v[88:91], v[96:99], v[26:29]
	v_mfma_f32_16x16x32_bf16 v[30:33], v[88:91], v[100:103], v[30:33]
	v_mfma_f32_16x16x32_bf16 v[34:37], v[92:95], v[96:99], v[34:37]
	v_mfma_f32_16x16x32_bf16 v[38:41], v[92:95], v[100:103], v[38:41]
	global_load_dwordx4 v[80:83], v[50:51], off offset:384
	global_load_dwordx4 v[84:87], v[56:57], off offset:384
	global_load_dwordx4 v[88:91], v[58:59], off offset:384
	global_load_dwordx4 v[92:95], v[52:53], off offset:384
	global_load_dwordx4 v[96:99], v[24:25], off offset:384
	global_load_dwordx4 v[100:103], v[54:55], off offset:384
	s_waitcnt vmcnt(12)
; #define LAS __attribute__((address_space(3)))
; #define LAS __attribute__((address_space(3)))
; __device__ __forceinline__ void ctx_slice_gemm(LAS unsigned char* lds, const bf16_t* A  , const bf16_t* Bt  , int K, ...
;     ...
; #pragma unroll 4
;     for (int k = 0; k < kw; k += 32) {
;         bf16x8 fa[4], fb[2];
; #pragma unroll
;         for (int i = 0; i < 4; ++i) fa[i] = *(const bf16x8*)(ap + i * a16 + k);
; #pragma unroll
;         for (int j = 0; j < 2; ++j) fb[j] = *(const bf16x8*)(bp + j * a16 + k);
; #pragma unroll
;         for (int i = 0; i < 4; ++i)
; #pragma unroll
;             for (int j = 0; j < 2; ++j) acc[i][j] = __builtin_amdgcn_mfma_f32_16x16x32_bf16(fa[i], fb[j], acc[i][j], 0, 0, 0);
;     }
;     LAS float* part = (LAS float*)lds;
; #pragma unroll
;     for (int i = 0; i < 4; ++i)
; #pragma unroll
;         for (int j = 0; j < 2; ++j)
; #pragma unroll
;             for (int q = 0; q < 4; ++q) part[((wid * 8 + i * 2 + j) * 4 + q) * 64 + lane] = acc[i][j][q];
;     __syncthreads();
	v_mfma_f32_16x16x32_bf16 v[62:65], v[104:107], v[120:123], v[62:65]
	v_mfma_f32_16x16x32_bf16 v[66:69], v[104:107], v[124:127], v[66:69]
	v_mfma_f32_16x16x32_bf16 v[70:73], v[108:111], v[120:123], v[70:73]
	v_mfma_f32_16x16x32_bf16 v[74:77], v[108:111], v[124:127], v[74:77]
	v_mfma_f32_16x16x32_bf16 v[26:29], v[112:115], v[120:123], v[26:29]
	v_mfma_f32_16x16x32_bf16 v[30:33], v[112:115], v[124:127], v[30:33]
	v_mfma_f32_16x16x32_bf16 v[34:37], v[116:119], v[120:123], v[34:37]
	v_mfma_f32_16x16x32_bf16 v[38:41], v[116:119], v[124:127], v[38:41]
	global_load_dwordx4 v[104:107], v[50:51], off offset:448
	global_load_dwordx4 v[108:111], v[56:57], off offset:448
	global_load_dwordx4 v[112:115], v[58:59], off offset:448
	global_load_dwordx4 v[116:119], v[52:53], off offset:448
	global_load_dwordx4 v[120:123], v[24:25], off offset:448
	global_load_dwordx4 v[124:127], v[54:55], off offset:448
	s_waitcnt vmcnt(12)
	v_mfma_f32_16x16x32_bf16 v[62:65], v[128:131], v[144:147], v[62:65]
	v_mfma_f32_16x16x32_bf16 v[66:69], v[128:131], v[148:151], v[66:69]
	v_mfma_f32_16x16x32_bf16 v[70:73], v[132:135], v[144:147], v[70:73]
	v_mfma_f32_16x16x32_bf16 v[74:77], v[132:135], v[148:151], v[74:77]
	v_mfma_f32_16x16x32_bf16 v[26:29], v[136:139], v[144:147], v[26:29]
	v_mfma_f32_16x16x32_bf16 v[30:33], v[136:139], v[148:151], v[30:33]
	v_mfma_f32_16x16x32_bf16 v[34:37], v[140:143], v[144:147], v[34:37]
	v_mfma_f32_16x16x32_bf16 v[38:41], v[140:143], v[148:151], v[38:41]
	global_load_dwordx4 v[128:131], v[50:51], off offset:512
	global_load_dwordx4 v[132:135], v[56:57], off offset:512
	global_load_dwordx4 v[136:139], v[58:59], off offset:512
	global_load_dwordx4 v[140:143], v[52:53], off offset:512
	global_load_dwordx4 v[144:147], v[24:25], off offset:512
	global_load_dwordx4 v[148:151], v[54:55], off offset:512
	s_waitcnt vmcnt(12)
	v_mfma_f32_16x16x32_bf16 v[62:65], v[80:83], v[96:99], v[62:65]
	v_mfma_f32_16x16x32_bf16 v[66:69], v[80:83], v[100:103], v[66:69]
	v_mfma_f32_16x16x32_bf16 v[70:73], v[84:87], v[96:99], v[70:73]
	v_mfma_f32_16x16x32_bf16 v[74:77], v[84:87], v[100:103], v[74:77]
	v_mfma_f32_16x16x32_bf16 v[26:29], v[88:91], v[96:99], v[26:29]
	v_mfma_f32_16x16x32_bf16 v[30:33], v[88:91], v[100:103], v[30:33]
	v_mfma_f32_16x16x32_bf16 v[34:37], v[92:95], v[96:99], v[34:37]
	v_mfma_f32_16x16x32_bf16 v[38:41], v[92:95], v[100:103], v[38:41]
	global_load_dwordx4 v[80:83], v[50:51], off offset:576
	global_load_dwordx4 v[84:87], v[56:57], off offset:576
	global_load_dwordx4 v[88:91], v[58:59], off offset:576
	global_load_dwordx4 v[92:95], v[52:53], off offset:576
	global_load_dwordx4 v[96:99], v[24:25], off offset:576
	global_load_dwordx4 v[100:103], v[54:55], off offset:576
	s_waitcnt vmcnt(12)
	v_mfma_f32_16x16x32_bf16 v[62:65], v[104:107], v[120:123], v[62:65]
	v_mfma_f32_16x16x32_bf16 v[66:69], v[104:107], v[124:127], v[66:69]
	v_mfma_f32_16x16x32_bf16 v[70:73], v[108:111], v[120:123], v[70:73]
	v_mfma_f32_16x16x32_bf16 v[74:77], v[108:111], v[124:127], v[74:77]
	v_mfma_f32_16x16x32_bf16 v[26:29], v[112:115], v[120:123], v[26:29]
	v_mfma_f32_16x16x32_bf16 v[30:33], v[112:115], v[124:127], v[30:33]
	v_mfma_f32_16x16x32_bf16 v[34:37], v[116:119], v[120:123], v[34:37]
	v_mfma_f32_16x16x32_bf16 v[38:41], v[116:119], v[124:127], v[38:41]
	global_load_dwordx4 v[104:107], v[50:51], off offset:640
	global_load_dwordx4 v[108:111], v[56:57], off offset:640
	global_load_dwordx4 v[112:115], v[58:59], off offset:640
	global_load_dwordx4 v[116:119], v[52:53], off offset:640
	global_load_dwordx4 v[120:123], v[24:25], off offset:640
	global_load_dwordx4 v[124:127], v[54:55], off offset:640
	s_waitcnt vmcnt(12)
	v_mfma_f32_16x16x32_bf16 v[62:65], v[128:131], v[144:147], v[62:65]
	v_mfma_f32_16x16x32_bf16 v[66:69], v[128:131], v[148:151], v[66:69]
	v_mfma_f32_16x16x32_bf16 v[70:73], v[132:135], v[144:147], v[70:73]
	v_mfma_f32_16x16x32_bf16 v[74:77], v[132:135], v[148:151], v[74:77]
	v_mfma_f32_16x16x32_bf16 v[26:29], v[136:139], v[144:147], v[26:29]
	v_mfma_f32_16x16x32_bf16 v[30:33], v[136:139], v[148:151], v[30:33]
	v_mfma_f32_16x16x32_bf16 v[34:37], v[140:143], v[144:147], v[34:37]
	v_mfma_f32_16x16x32_bf16 v[38:41], v[140:143], v[148:151], v[38:41]
	s_waitcnt vmcnt(6)
	v_mfma_f32_16x16x32_bf16 v[62:65], v[80:83], v[96:99], v[62:65]
	v_mfma_f32_16x16x32_bf16 v[66:69], v[80:83], v[100:103], v[66:69]
	v_mfma_f32_16x16x32_bf16 v[70:73], v[84:87], v[96:99], v[70:73]
	v_mfma_f32_16x16x32_bf16 v[74:77], v[84:87], v[100:103], v[74:77]
	v_mfma_f32_16x16x32_bf16 v[26:29], v[88:91], v[96:99], v[26:29]
	v_mfma_f32_16x16x32_bf16 v[30:33], v[88:91], v[100:103], v[30:33]
	v_mfma_f32_16x16x32_bf16 v[34:37], v[92:95], v[96:99], v[34:37]
	v_mfma_f32_16x16x32_bf16 v[38:41], v[92:95], v[100:103], v[38:41]
	s_waitcnt vmcnt(0)
	v_mfma_f32_16x16x32_bf16 v[62:65], v[104:107], v[120:123], v[62:65]
	v_mfma_f32_16x16x32_bf16 v[66:69], v[104:107], v[124:127], v[66:69]
	v_mfma_f32_16x16x32_bf16 v[70:73], v[108:111], v[120:123], v[70:73]
	v_mfma_f32_16x16x32_bf16 v[74:77], v[108:111], v[124:127], v[74:77]
	v_mfma_f32_16x16x32_bf16 v[26:29], v[112:115], v[120:123], v[26:29]
	v_mfma_f32_16x16x32_bf16 v[30:33], v[112:115], v[124:127], v[30:33]
	v_mfma_f32_16x16x32_bf16 v[34:37], v[116:119], v[120:123], v[34:37]
	v_mfma_f32_16x16x32_bf16 v[38:41], v[116:119], v[124:127], v[38:41]
	v_and_b32_e32 v52, 63, v61
	v_lshl_add_u32 v52, v52, 2, 0
	v_lshl_add_u32 v53, s0, 13, v52
	v_or_b32_e32 v13, s13, v60
	v_lshlrev_b32_e32 v176, 2, v13
	s_lshl_b32 s0, s0, 10
	v_add_u32_e32 v14, s0, v52
	s_nop 7
	ds_write2st64_b32 v53, v62, v63 offset1:1
	ds_write2st64_b32 v53, v64, v65 offset0:2 offset1:3
	ds_write2st64_b32 v53, v66, v67 offset0:4 offset1:5
	ds_write2st64_b32 v53, v68, v69 offset0:6 offset1:7
	ds_write2st64_b32 v53, v70, v71 offset0:8 offset1:9
	ds_write2st64_b32 v53, v72, v73 offset0:10 offset1:11
	ds_write2st64_b32 v53, v74, v75 offset0:12 offset1:13
	ds_write2st64_b32 v53, v76, v77 offset0:14 offset1:15
	ds_write2st64_b32 v53, v26, v27 offset0:16 offset1:17
	ds_write2st64_b32 v53, v28, v29 offset0:18 offset1:19
	ds_write2st64_b32 v53, v30, v31 offset0:20 offset1:21
	ds_write2st64_b32 v53, v32, v33 offset0:22 offset1:23
	ds_write2st64_b32 v53, v34, v35 offset0:24 offset1:25
	ds_write2st64_b32 v53, v36, v37 offset0:26 offset1:27
	ds_write2st64_b32 v53, v38, v39 offset0:28 offset1:29
	ds_write2st64_b32 v53, v40, v41 offset0:30 offset1:31
	v_lshl_add_u64 v[0:1], s[4:5], 0, v[176:177]
	s_waitcnt lgkmcnt(0)
	s_barrier
; __device__ __forceinline__ unsigned pkbf(float lo, float hi) { return pg8::cvt_pk_bf16(lo, hi); }
; __device__ __forceinline__ void ctx_slice_gemm(LAS unsigned char* lds, const bf16_t* A  , const bf16_t* Bt  , int K, ...
;     ...
;         const int t = wid, rgi = t >> 1, cg = t & 1, col = col0 + 16 * cg + r16;
;         const float gt = gate2[col];
;         const bool nxt = ng != nullptr;
;         const float gs = nxt ? ng[col] * (1.f + nsc2[col]) : 0.f;
; #pragma unroll
;         for (int q = 0; q < 4; ++q) {
;             float s = 0.f;
; #pragma unroll
;             for (int w = 0; w < 8; ++w) s += part[((w * 8 + t) * 4 + q) * 64 + lane];
;             const int rr = row0 + 16 * rgi + 4 * g4 + q;
;             const float x = res_ctx[(size_t)rr * DM + col] + gt * s;
;             dst_ctx[(size_t)rr * DM + col] = x;
;             if (nxt) {
;                 xg[(size_t)(MLAT + rr) * DM + col] = (bf16_t)(pkbf(x * gs, 0.f) & 0xffffu);
;                 float ss = x * x;
;                 ss += __shfl_xor(ss, 1); ss += __shfl_xor(ss, 2); ss += __shfl_xor(ss, 4); ss += __shfl_xor(ss, 8);
;                 if (r16 == 0) unsafeAtomicAdd(rowsq_next + MLAT + rr, ss);
;             }
	flat_load_dword v8, v[0:1]
	v_lshrrev_b32_e32 v0, 2, v61
	v_and_or_b32 v0, v0, 12, s1
	v_ashrrev_i32_e32 v1, 31, v0
	v_lshlrev_b64 v[2:3], 12, v[0:1]
	v_lshl_add_u64 v[2:3], s[22:23], 0, v[2:3]
	v_lshl_add_u64 v[2:3], v[2:3], 0, v[176:177]
	flat_load_dword v15, v[2:3]
	v_add_co_u32_e32 v80, vcc, 0x1000, v2
	s_nop 1
	v_addc_co_u32_e32 v81, vcc, 0, v3, vcc
	flat_load_dword v90, v[80:81]
	v_add_co_u32_e32 v82, vcc, 0x2000, v2
	s_nop 1
	v_addc_co_u32_e32 v83, vcc, 0, v3, vcc
	flat_load_dword v91, v[82:83]
	v_add_co_u32_e32 v84, vcc, 0x3000, v2
	s_nop 1
	v_addc_co_u32_e32 v85, vcc, 0, v3, vcc
	flat_load_dword v92, v[84:85]
	v_lshl_add_u64 v[4:5], s[8:9], 0, v[176:177]
	flat_load_dword v12, v[4:5]
	global_load_dword v16, v176, s[6:7]
	ds_read2st64_b32 v[4:5], v14 offset1:32
	ds_read2st64_b32 v[6:7], v14 offset0:64 offset1:96
	ds_read2st64_b32 v[10:11], v14 offset0:128 offset1:160
	v_cmp_eq_u32_e64 s[0:1], 0, v60
	s_waitcnt lgkmcnt(0)
	v_add_f32_e32 v4, 0, v4
	v_add_f32_e32 v9, v4, v5
	ds_read2st64_b32 v[4:5], v14 offset0:192 offset1:224
	v_add_f32_e32 v6, v9, v6
	v_add_f32_e32 v6, v6, v7
	v_add_f32_e32 v6, v6, v10
	v_add_f32_e32 v6, v6, v11
	s_waitcnt lgkmcnt(0)
	v_add_f32_e32 v4, v6, v4
	v_and_b32_e32 v6, 64, v229
	v_add_f32_e32 v4, v4, v5
	v_xor_b32_e32 v5, 1, v229
	v_add_u32_e32 v7, 64, v6
	v_cmp_lt_i32_e32 vcc, v5, v7
	s_waitcnt vmcnt(0)
	v_fmac_f32_e32 v15, v8, v4
	v_cndmask_b32_e32 v5, v229, v5, vcc
	v_mul_f32_e32 v4, v15, v15
	v_lshlrev_b32_e32 v9, 2, v5
	ds_bpermute_b32 v6, v9, v4
	v_xor_b32_e32 v5, 2, v229
	v_cmp_lt_i32_e32 vcc, v5, v7
	flat_store_dword v[2:3], v15
	v_xor_b32_e32 v2, 4, v229
	v_cndmask_b32_e32 v5, v229, v5, vcc
	s_waitcnt lgkmcnt(0)
	v_fmac_f32_e32 v6, v15, v15
	v_lshlrev_b32_e32 v10, 2, v5
	ds_bpermute_b32 v11, v10, v6
	v_cmp_lt_i32_e32 vcc, v2, v7
	v_add_f32_e32 v4, 1.0, v12
	v_mul_f32_e32 v12, v16, v4
	v_cndmask_b32_e32 v2, v229, v2, vcc
	s_waitcnt lgkmcnt(0)
	v_add_f32_e32 v6, v6, v11
	v_lshlrev_b32_e32 v11, 2, v2
	v_lshlrev_b32_e32 v4, 1, v13
	v_mov_b32_e32 v5, v177
	ds_bpermute_b32 v13, v11, v6
	v_mul_f32_e32 v2, v12, v15
	v_lshl_add_u64 v[4:5], s[24:25], 0, v[4:5]
	v_cvt_pk_bf16_f32 v15, v2, v177
	v_lshlrev_b64 v[2:3], 11, v[0:1]
	v_lshl_add_u64 v[2:3], v[4:5], 0, v[2:3]
	v_xor_b32_e32 v4, 8, v229
	v_cmp_lt_i32_e32 vcc, v4, v7
	s_waitcnt lgkmcnt(0)
	v_add_f32_e32 v6, v6, v13
	v_cndmask_b32_e32 v4, v229, v4, vcc
	v_lshlrev_b32_e32 v13, 2, v4
	ds_bpermute_b32 v7, v13, v6
	v_add_co_u32_e32 v4, vcc, s12, v2
	s_nop 1
	v_addc_co_u32_e32 v5, vcc, 0, v3, vcc
	flat_store_short v[4:5], v15
	s_and_saveexec_b64 s[12:13], s[0:1]
	s_cbranch_execz .LBB0_1279
	s_waitcnt lgkmcnt(0)
	v_add_f32_e32 v15, v6, v7
	v_lshl_add_u64 v[6:7], v[0:1], 2, s[10:11]
	flat_atomic_add_f32 v[6:7], v15
.LBB0_1279:
	s_or_b64 exec, exec, s[12:13]
	s_waitcnt lgkmcnt(0)
	ds_read2st64_b32 v[6:7], v14 offset0:1 offset1:33
	s_waitcnt lgkmcnt(0)
	v_add_f32_e32 v1, 0, v6
	v_add_f32_e32 v1, v1, v7
	ds_read2st64_b32 v[6:7], v14 offset0:65 offset1:97
	s_waitcnt lgkmcnt(0)
	v_add_f32_e32 v1, v1, v6
	v_add_f32_e32 v1, v1, v7
	ds_read2st64_b32 v[6:7], v14 offset0:129 offset1:161
	s_waitcnt lgkmcnt(0)
	v_add_f32_e32 v1, v1, v6
	v_add_f32_e32 v1, v1, v7
	ds_read2st64_b32 v[6:7], v14 offset0:193 offset1:225
	s_waitcnt lgkmcnt(0)
	v_add_f32_e32 v1, v1, v6
	v_or_b32_e32 v6, 1, v0
	v_add_f32_e32 v1, v1, v7
	v_ashrrev_i32_e32 v7, 31, v6
	v_lshlrev_b64 v[16:17], 12, v[6:7]
	v_lshl_add_u64 v[16:17], s[22:23], 0, v[16:17]
	v_lshl_add_u64 v[16:17], v[16:17], 0, v[176:177]
	v_mov_b32_e32 v15, v90
	v_fmac_f32_e32 v15, v8, v1
	v_mul_f32_e32 v1, v12, v15
	flat_store_dword v[16:17], v15
	v_cvt_pk_bf16_f32 v1, v1, v177
	flat_store_short v[4:5], v1 offset:2048
	v_mul_f32_e32 v1, v15, v15
	ds_bpermute_b32 v1, v9, v1
	s_waitcnt lgkmcnt(0)
	v_fmac_f32_e32 v1, v15, v15
	ds_bpermute_b32 v4, v10, v1
	s_waitcnt lgkmcnt(0)
	v_add_f32_e32 v1, v1, v4
	ds_bpermute_b32 v4, v11, v1
	s_waitcnt lgkmcnt(0)
	v_add_f32_e32 v1, v1, v4
	ds_bpermute_b32 v4, v13, v1
	s_and_saveexec_b64 s[12:13], s[0:1]
	s_cbranch_execz .LBB0_1281
	s_waitcnt lgkmcnt(0)
	v_add_f32_e32 v1, v1, v4
	v_lshl_add_u64 v[4:5], v[6:7], 2, s[10:11]
	flat_atomic_add_f32 v[4:5], v1
; __device__ __forceinline__ unsigned pkbf(float lo, float hi) { return pg8::cvt_pk_bf16(lo, hi); }
; __device__ __forceinline__ void ctx_slice_gemm(LAS unsigned char* lds, const bf16_t* A  , const bf16_t* Bt  , int K, ...
;     ...
;         for (int q = 0; q < 4; ++q) {
;             float s = 0.f;
; #pragma unroll
;             for (int w = 0; w < 8; ++w) s += part[((w * 8 + t) * 4 + q) * 64 + lane];
;             const int rr = row0 + 16 * rgi + 4 * g4 + q;
;             const float x = res_ctx[(size_t)rr * DM + col] + gt * s;
;             dst_ctx[(size_t)rr * DM + col] = x;
;             if (nxt) {
;                 xg[(size_t)(MLAT + rr) * DM + col] = (bf16_t)(pkbf(x * gs, 0.f) & 0xffffu);
;                 float ss = x * x;
;                 ss += __shfl_xor(ss, 1); ss += __shfl_xor(ss, 2); ss += __shfl_xor(ss, 4); ss += __shfl_xor(ss, 8);
;                 if (r16 == 0) unsafeAtomicAdd(rowsq_next + MLAT + rr, ss);
;             }
.LBB0_1281:
	s_or_b64 exec, exec, s[12:13]
	s_waitcnt lgkmcnt(0)
	ds_read2st64_b32 v[4:5], v14 offset0:2 offset1:34
	s_mov_b32 s12, 0x2001000
	v_add_co_u32_e32 v2, vcc, s12, v2
	s_waitcnt lgkmcnt(0)
	v_add_f32_e32 v1, 0, v4
	v_add_f32_e32 v1, v1, v5
	ds_read2st64_b32 v[4:5], v14 offset0:66 offset1:98
	v_addc_co_u32_e32 v3, vcc, 0, v3, vcc
	s_waitcnt lgkmcnt(0)
	v_add_f32_e32 v1, v1, v4
	v_add_f32_e32 v1, v1, v5
	ds_read2st64_b32 v[4:5], v14 offset0:130 offset1:162
	s_waitcnt lgkmcnt(0)
	v_add_f32_e32 v1, v1, v4
	v_add_f32_e32 v1, v1, v5
	ds_read2st64_b32 v[4:5], v14 offset0:194 offset1:226
	s_waitcnt lgkmcnt(0)
	v_add_f32_e32 v1, v1, v4
	v_or_b32_e32 v4, 2, v0
	v_add_f32_e32 v1, v1, v5
	v_ashrrev_i32_e32 v5, 31, v4
	v_lshlrev_b64 v[6:7], 12, v[4:5]
	v_lshl_add_u64 v[6:7], s[22:23], 0, v[6:7]
	v_lshl_add_u64 v[6:7], v[6:7], 0, v[176:177]
	v_mov_b32_e32 v15, v91
	v_fmac_f32_e32 v15, v8, v1
	v_mul_f32_e32 v1, v12, v15
	flat_store_dword v[6:7], v15
	v_cvt_pk_bf16_f32 v1, v1, v177
	flat_store_short v[2:3], v1
	v_mul_f32_e32 v1, v15, v15
	ds_bpermute_b32 v1, v9, v1
	s_waitcnt lgkmcnt(0)
	v_fmac_f32_e32 v1, v15, v15
	ds_bpermute_b32 v6, v10, v1
	s_waitcnt lgkmcnt(0)
	v_add_f32_e32 v1, v1, v6
	ds_bpermute_b32 v6, v11, v1
	s_waitcnt lgkmcnt(0)
	v_add_f32_e32 v1, v1, v6
	ds_bpermute_b32 v6, v13, v1
	s_and_saveexec_b64 s[12:13], s[0:1]
	s_cbranch_execz .LBB0_1283
	s_waitcnt lgkmcnt(0)
	v_add_f32_e32 v1, v1, v6
	v_lshl_add_u64 v[4:5], v[4:5], 2, s[10:11]
	flat_atomic_add_f32 v[4:5], v1
.LBB0_1283:
	s_or_b64 exec, exec, s[12:13]
	ds_read2st64_b32 v[4:5], v14 offset0:3 offset1:35
	v_or_b32_e32 v0, 3, v0
	s_waitcnt lgkmcnt(0)
	v_add_f32_e32 v1, 0, v4
	v_add_f32_e32 v1, v1, v5
	ds_read2st64_b32 v[4:5], v14 offset0:67 offset1:99
	s_waitcnt lgkmcnt(0)
	v_add_f32_e32 v1, v1, v4
	v_add_f32_e32 v1, v1, v5
	ds_read2st64_b32 v[4:5], v14 offset0:131 offset1:163
	s_waitcnt lgkmcnt(0)
	v_add_f32_e32 v1, v1, v4
	v_add_f32_e32 v1, v1, v5
	ds_read2st64_b32 v[4:5], v14 offset0:195 offset1:227
	s_waitcnt lgkmcnt(0)
	v_add_f32_e32 v1, v1, v4
	v_add_f32_e32 v6, v1, v5
	v_ashrrev_i32_e32 v1, 31, v0
	v_lshlrev_b64 v[4:5], 12, v[0:1]
	v_lshl_add_u64 v[4:5], s[22:23], 0, v[4:5]
	v_lshl_add_u64 v[4:5], v[4:5], 0, v[176:177]
	v_mov_b32_e32 v7, v92
	v_fmac_f32_e32 v7, v8, v6
	flat_store_dword v[4:5], v7
	v_mul_f32_e32 v4, v12, v7
	v_cvt_pk_bf16_f32 v4, v4, v177
	flat_store_short v[2:3], v4 offset:2048
	v_mul_f32_e32 v2, v7, v7
	ds_bpermute_b32 v2, v9, v2
	s_waitcnt lgkmcnt(0)
	v_fmac_f32_e32 v2, v7, v7
	ds_bpermute_b32 v3, v10, v2
	s_waitcnt lgkmcnt(0)
	v_add_f32_e32 v2, v2, v3
	ds_bpermute_b32 v3, v11, v2
	s_waitcnt lgkmcnt(0)
	v_add_f32_e32 v2, v2, v3
	ds_bpermute_b32 v3, v13, v2
	s_and_saveexec_b64 s[12:13], s[0:1]
	s_cbranch_execz .LBB0_1276
	s_waitcnt lgkmcnt(0)
	v_add_f32_e32 v2, v2, v3
	v_lshl_add_u64 v[0:1], v[0:1], 2, s[10:11]
	flat_atomic_add_f32 v[0:1], v2
	s_branch .LBB0_1276
